# tail strip write-back: the four residual loads issued together
# baseline (speedup 1.0000x reference)
; #define LAS __attribute__((address_space(3)))
; __device__ __forceinline__ f32x4 ld_bf4(const bf16* q) { const v2u w = *(const v2u*)q; return (f32x4){bf_lo(w.x), bf_hi(w.x), bf_lo(w.y), bf_hi(w.y)}; }
; __device__ __forceinline__ void st_bf4(bf16* q, const f32x4 v) { v2u w; w.x = cvt_pk_bf16(v.x, v.y); w.y = cvt_pk_bf16(v.z, v.w); *(v2u*)q = w; }
; __device__ __forceinline__ void tail_resid(const bf16* __restrict__ A, const bf16* __restrict__ Bt, int K, unsigned char* ws, int slot, float amul, LAS unsigned char* lds, int lane, int wave) {
;     ...
;         __syncthreads();
; #pragma unroll
;         for (int t = 0; t < 4; ++t) *(LAS f32x4*)(lds + ((wave * 4 + t) * 64 + lane) * 16) = acc[t];
;         __syncthreads();
;         if (wave == 0) {
; #pragma unroll
;             for (int t = 0; t < 4; ++t) { f32x4 s = acc[t];
; #pragma unroll
;                 for (int w = 1; w < 8; ++w) s += *(LAS f32x4*)(lds + ((w * 4 + t) * 64 + lane) * 16);
;                 acc[t] = s; }
;             const int row = MT0 + 16 * rs + fr;
;             bf16* xb = (bf16*)(ws + WS_XB) + (size_t)row * D + 64 * cs + 4 * fq;
;             float ssq = 0.f;
; #pragma unroll
;             for (int t = 0; t < 4; ++t) { const f32x4 v = ld_bf4(xb + 16 * t) + acc[t] * amul; st_bf4(xb + 16 * t, v);
;                 if (slot >= 0) ssq += (v.x * v.x + v.y * v.y) + (v.z * v.z + v.w * v.w); }
.Ltr_done:
	v_add_u32_e32 v0, s17, v46
	s_and_b64 vcc, exec, s[0:1]
	s_waitcnt lgkmcnt(0)
	s_barrier
	ds_write_b128 v0, v[14:17]
	ds_write_b128 v0, v[10:13] offset:1024
	ds_write_b128 v0, v[6:9] offset:2048
	ds_write_b128 v0, v[2:5] offset:3072
	s_waitcnt lgkmcnt(0)
	s_barrier
	s_cbranch_vccz .LBB0_1403
	v_add_u32_e32 v0, 0, v46
	ds_read_b128 v[32:35], v0 offset:4096
	s_lshl_b32 s94, s14, 1
	v_mov_b32_e32 v29, v1
	s_andn2_b64 vcc, exec, s[2:3]
	s_waitcnt lgkmcnt(0)
	v_pk_add_f32 v[34:35], v[16:17], v[34:35]
	v_pk_add_f32 v[32:33], v[14:15], v[32:33]
	ds_read_b128 v[14:17], v0 offset:8192
	s_waitcnt lgkmcnt(0)
	v_pk_add_f32 v[34:35], v[34:35], v[16:17]
	v_pk_add_f32 v[32:33], v[32:33], v[14:15]
	ds_read_b128 v[14:17], v0 offset:12288
	s_waitcnt lgkmcnt(0)
	v_pk_add_f32 v[34:35], v[34:35], v[16:17]
	v_pk_add_f32 v[32:33], v[32:33], v[14:15]
	ds_read_b128 v[14:17], v0 offset:16384
	s_waitcnt lgkmcnt(0)
	v_pk_add_f32 v[34:35], v[34:35], v[16:17]
	v_pk_add_f32 v[32:33], v[32:33], v[14:15]
	ds_read_b128 v[14:17], v0 offset:20480
	s_waitcnt lgkmcnt(0)
	v_pk_add_f32 v[34:35], v[34:35], v[16:17]
	v_pk_add_f32 v[32:33], v[32:33], v[14:15]
	ds_read_b128 v[14:17], v0 offset:24576
	s_waitcnt lgkmcnt(0)
	v_pk_add_f32 v[34:35], v[34:35], v[16:17]
	v_pk_add_f32 v[32:33], v[32:33], v[14:15]
	ds_read_b128 v[14:17], v0 offset:28672
	s_waitcnt lgkmcnt(0)
	v_pk_add_f32 v[34:35], v[34:35], v[16:17]
	v_pk_add_f32 v[36:37], v[32:33], v[14:15]
	ds_read_b128 v[14:17], v0 offset:5120
	s_waitcnt lgkmcnt(0)
	v_pk_add_f32 v[16:17], v[12:13], v[16:17]
	v_pk_add_f32 v[14:15], v[10:11], v[14:15]
	ds_read_b128 v[10:13], v0 offset:9216
	s_waitcnt lgkmcnt(0)
	v_pk_add_f32 v[16:17], v[16:17], v[12:13]
	v_pk_add_f32 v[14:15], v[14:15], v[10:11]
	ds_read_b128 v[10:13], v0 offset:13312
	s_waitcnt lgkmcnt(0)
	v_pk_add_f32 v[16:17], v[16:17], v[12:13]
	v_pk_add_f32 v[14:15], v[14:15], v[10:11]
	ds_read_b128 v[10:13], v0 offset:17408
	s_waitcnt lgkmcnt(0)
	v_pk_add_f32 v[16:17], v[16:17], v[12:13]
	v_pk_add_f32 v[14:15], v[14:15], v[10:11]
	ds_read_b128 v[10:13], v0 offset:21504
	s_waitcnt lgkmcnt(0)
	v_pk_add_f32 v[16:17], v[16:17], v[12:13]
	v_pk_add_f32 v[14:15], v[14:15], v[10:11]
	ds_read_b128 v[10:13], v0 offset:25600
	s_waitcnt lgkmcnt(0)
	v_pk_add_f32 v[16:17], v[16:17], v[12:13]
	v_pk_add_f32 v[14:15], v[14:15], v[10:11]
	ds_read_b128 v[10:13], v0 offset:29696
	s_waitcnt lgkmcnt(0)
	v_pk_add_f32 v[16:17], v[16:17], v[12:13]
	v_pk_add_f32 v[32:33], v[14:15], v[10:11]
	ds_read_b128 v[10:13], v0 offset:6144
	s_waitcnt lgkmcnt(0)
	v_pk_add_f32 v[12:13], v[8:9], v[12:13]
	v_pk_add_f32 v[10:11], v[6:7], v[10:11]
	ds_read_b128 v[6:9], v0 offset:10240
	s_waitcnt lgkmcnt(0)
	v_pk_add_f32 v[12:13], v[12:13], v[8:9]
	v_pk_add_f32 v[10:11], v[10:11], v[6:7]
	ds_read_b128 v[6:9], v0 offset:14336
	s_waitcnt lgkmcnt(0)
	v_pk_add_f32 v[12:13], v[12:13], v[8:9]
	v_pk_add_f32 v[10:11], v[10:11], v[6:7]
	ds_read_b128 v[6:9], v0 offset:18432
	s_waitcnt lgkmcnt(0)
	v_pk_add_f32 v[12:13], v[12:13], v[8:9]
	v_pk_add_f32 v[10:11], v[10:11], v[6:7]
	ds_read_b128 v[6:9], v0 offset:22528
	s_waitcnt lgkmcnt(0)
	v_pk_add_f32 v[12:13], v[12:13], v[8:9]
	v_pk_add_f32 v[10:11], v[10:11], v[6:7]
	ds_read_b128 v[6:9], v0 offset:26624
	s_waitcnt lgkmcnt(0)
	v_pk_add_f32 v[12:13], v[12:13], v[8:9]
	v_pk_add_f32 v[10:11], v[10:11], v[6:7]
	ds_read_b128 v[6:9], v0 offset:30720
	s_waitcnt lgkmcnt(0)
	v_pk_add_f32 v[12:13], v[12:13], v[8:9]
	v_pk_add_f32 v[14:15], v[10:11], v[6:7]
	ds_read_b128 v[6:9], v0 offset:7168
	s_waitcnt lgkmcnt(0)
	v_pk_add_f32 v[8:9], v[4:5], v[8:9]
	v_pk_add_f32 v[6:7], v[2:3], v[6:7]
	ds_read_b128 v[2:5], v0 offset:11264
	s_waitcnt lgkmcnt(0)
	v_pk_add_f32 v[8:9], v[8:9], v[4:5]
	v_pk_add_f32 v[6:7], v[6:7], v[2:3]
	ds_read_b128 v[2:5], v0 offset:15360
	s_waitcnt lgkmcnt(0)
	v_pk_add_f32 v[8:9], v[8:9], v[4:5]
	v_pk_add_f32 v[6:7], v[6:7], v[2:3]
	ds_read_b128 v[2:5], v0 offset:19456
	s_waitcnt lgkmcnt(0)
	v_pk_add_f32 v[8:9], v[8:9], v[4:5]
	v_pk_add_f32 v[6:7], v[6:7], v[2:3]
	ds_read_b128 v[2:5], v0 offset:23552
	s_waitcnt lgkmcnt(0)
	v_pk_add_f32 v[8:9], v[8:9], v[4:5]
	v_pk_add_f32 v[6:7], v[6:7], v[2:3]
	ds_read_b128 v[2:5], v0 offset:27648
	s_waitcnt lgkmcnt(0)
	v_pk_add_f32 v[8:9], v[8:9], v[4:5]
	v_pk_add_f32 v[6:7], v[6:7], v[2:3]
	ds_read_b128 v[2:5], v0 offset:31744
	s_waitcnt lgkmcnt(0)
	v_pk_add_f32 v[2:3], v[6:7], v[2:3]
	v_lshlrev_b64 v[6:7], 11, v[30:31]
	v_lshl_add_u64 v[6:7], s[90:91], 0, v[6:7]
	v_lshl_add_u64 v[6:7], v[6:7], 0, s[94:95]
	v_lshl_add_u64 v[10:11], v[6:7], 0, v[28:29]
	global_load_dwordx2 v[6:7], v[10:11], off
	global_load_dwordx2 v[56:57], v[10:11], off offset:32
	global_load_dwordx2 v[58:59], v[10:11], off offset:64
	global_load_dwordx2 v[60:61], v[10:11], off offset:96
	v_pk_add_f32 v[4:5], v[8:9], v[4:5]
	s_waitcnt vmcnt(3)
	v_lshlrev_b32_e32 v8, 16, v6
	v_and_b32_e32 v9, 0xffff0000, v6
	v_lshlrev_b32_e32 v6, 16, v7
	v_and_b32_e32 v7, 0xffff0000, v7
	v_pk_add_f32 v[6:7], v[34:35], v[6:7]
	v_pk_add_f32 v[8:9], v[36:37], v[8:9]
	v_cvt_pk_bf16_f32 v35, v6, v7
	s_nop 0
	v_cvt_pk_bf16_f32 v34, v8, v9
	global_store_dwordx2 v[10:11], v[34:35], off
	s_waitcnt vmcnt(3)
	v_mov_b32_e32 v34, v56
	v_mov_b32_e32 v35, v57
	v_lshlrev_b32_e32 v36, 16, v34
	v_and_b32_e32 v37, 0xffff0000, v34
	v_lshlrev_b32_e32 v34, 16, v35
	v_and_b32_e32 v35, 0xffff0000, v35
	v_pk_add_f32 v[16:17], v[16:17], v[34:35]
	v_pk_add_f32 v[32:33], v[32:33], v[36:37]
	v_cvt_pk_bf16_f32 v35, v16, v17
	s_nop 0
	v_cvt_pk_bf16_f32 v34, v32, v33
	global_store_dwordx2 v[10:11], v[34:35], off offset:32
	s_waitcnt vmcnt(3)
	v_mov_b32_e32 v34, v58
	v_mov_b32_e32 v35, v59
	v_lshlrev_b32_e32 v36, 16, v34
	v_and_b32_e32 v37, 0xffff0000, v34
	v_lshlrev_b32_e32 v34, 16, v35
	v_and_b32_e32 v35, 0xffff0000, v35
	v_pk_add_f32 v[12:13], v[12:13], v[34:35]
	v_pk_add_f32 v[14:15], v[14:15], v[36:37]
	v_cvt_pk_bf16_f32 v35, v12, v13
	s_nop 0
	v_cvt_pk_bf16_f32 v34, v14, v15
	global_store_dwordx2 v[10:11], v[34:35], off offset:64
	s_waitcnt vmcnt(3)
	v_mov_b32_e32 v34, v60
	v_mov_b32_e32 v35, v61
	v_lshlrev_b32_e32 v36, 16, v34
	v_and_b32_e32 v37, 0xffff0000, v34
	v_lshlrev_b32_e32 v34, 16, v35
	v_and_b32_e32 v35, 0xffff0000, v35
	v_pk_add_f32 v[4:5], v[4:5], v[34:35]
	v_pk_add_f32 v[2:3], v[2:3], v[36:37]
	v_cvt_pk_bf16_f32 v35, v4, v5
	s_nop 0
	v_cvt_pk_bf16_f32 v34, v2, v3
	global_store_dwordx2 v[10:11], v[34:35], off offset:96
	s_cbranch_vccnz .LBB0_1403
; __device__ __forceinline__ float shfl_xor_l(float v, int m, int lane) { return __int_as_float(__builtin_amdgcn_ds_bpermute((lane ^ m) << 2, __float_as_int(v))); }
; __device__ __forceinline__ void tail_resid(const bf16* __restrict__ A, const bf16* __restrict__ Bt, int K, unsigned char* ws, int slot, float amul, LAS unsigned char* lds, int lane, int wave) {
;     ...
;                 if (slot >= 0) ssq += (v.x * v.x + v.y * v.y) + (v.z * v.z + v.w * v.w); }
;             if (slot >= 0) { ssq += shfl_xor_l(ssq, 16, lane); ssq += shfl_xor_l(ssq, 32, lane); if (fq == 0) ((float*)(ws + WS_SS))[((size_t)slot * M + row) * 16 + cs] = ssq; }
	v_mul_f32_e32 v0, v9, v9
	v_mul_f32_e32 v7, v7, v7
	v_fmac_f32_e32 v0, v8, v8
	v_fmac_f32_e32 v7, v6, v6
	v_add_f32_e32 v0, v0, v7
	v_mul_f32_e32 v6, v33, v33
	v_mul_f32_e32 v7, v17, v17
	v_fmac_f32_e32 v6, v32, v32
	v_fmac_f32_e32 v7, v16, v16
	v_add_f32_e32 v6, v6, v7
	v_add_f32_e32 v0, v0, v6
	v_mul_f32_e32 v6, v15, v15
	v_mul_f32_e32 v7, v13, v13
	v_mul_f32_e32 v3, v3, v3
	v_fmac_f32_e32 v6, v14, v14
	v_fmac_f32_e32 v7, v12, v12
	v_fmac_f32_e32 v3, v2, v2
	v_mul_f32_e32 v2, v5, v5
	v_add_f32_e32 v6, v6, v7
	v_fmac_f32_e32 v2, v4, v4
	v_add_f32_e32 v0, v0, v6
	v_add_f32_e32 v2, v3, v2
	v_add_f32_e32 v0, v0, v2
	ds_bpermute_b32 v2, v44, v0
	s_waitcnt lgkmcnt(0)
	v_add_f32_e32 v0, v0, v2
	ds_bpermute_b32 v2, v45, v0
	s_and_saveexec_b64 s[14:15], s[4:5]
	s_cbranch_execz .LBB0_1402
	v_lshl_add_u64 v[4:5], s[6:7], 0, v[30:31]
	v_readlane_b32 s20, v252, 23
	v_lshlrev_b64 v[4:5], 6, v[4:5]
	v_readlane_b32 s21, v252, 24
	s_lshl_b32 s94, s18, 2
	s_waitcnt lgkmcnt(0)
	v_add_f32_e32 v0, v0, v2
	v_lshl_add_u64 v[4:5], s[20:21], 0, v[4:5]
	v_lshl_add_u64 v[4:5], v[4:5], 0, s[94:95]
	global_store_dword v[4:5], v0, off
	s_branch .LBB0_1402
